# prompt chain: LayerNorm-statistic reductions via DPP adds, partial-tile and n-update LDS reductions batched (fewer dependent LDS round trips per chunk)
# speedup vs baseline: 1.0570x; 1.0129x over previous
.LBB0_886:
	s_or_b64 exec, exec, s[74:75]
	v_lshlrev_b32_e32 v100, 16, v92
	v_and_b32_e32 v92, 0xffff0000, v92
	s_waitcnt lgkmcnt(0)
	v_lshlrev_b32_e32 v101, 16, v93
	v_and_b32_e32 v93, 0xffff0000, v93
	v_mul_f32_e32 v92, v113, v92
	v_mul_f32_e32 v93, v115, v93
	v_lshlrev_b32_e32 v102, 16, v94
	v_and_b32_e32 v94, 0xffff0000, v94
	v_fmac_f32_e32 v92, v112, v100
	v_fmac_f32_e32 v93, v114, v101
	v_add_f32_e32 v92, v92, v93
	v_mul_f32_e32 v93, v109, v94
	v_lshlrev_b32_e32 v103, 16, v95
	v_and_b32_e32 v95, 0xffff0000, v95
	v_fmac_f32_e32 v93, v108, v102
	v_add_f32_e32 v92, v92, v93
	v_mul_f32_e32 v93, v111, v95
	v_fmac_f32_e32 v93, v110, v103
	v_and_b32_e32 v94, 0xffff0000, v96
	v_add_f32_e32 v92, v93, v92
	v_lshlrev_b32_e32 v93, 16, v96
	v_and_b32_e32 v96, 0xffff0000, v97
	v_mul_f32_e32 v94, v121, v94
	v_lshlrev_b32_e32 v95, 16, v97
	v_fmac_f32_e32 v94, v120, v93
	v_mul_f32_e32 v93, v123, v96
	v_lshlrev_b32_e32 v97, 16, v98
	v_and_b32_e32 v98, 0xffff0000, v98
	v_fmac_f32_e32 v93, v122, v95
	v_add_f32_e32 v93, v94, v93
	v_mul_f32_e32 v94, v117, v98
	v_lshlrev_b32_e32 v100, 16, v99
	v_and_b32_e32 v99, 0xffff0000, v99
	v_fmac_f32_e32 v94, v116, v97
	v_add_f32_e32 v93, v93, v94
	v_mul_f32_e32 v94, v119, v99
	v_fmac_f32_e32 v94, v118, v100
	v_add_f32_e32 v92, 0, v92
	v_add_f32_e32 v93, v94, v93
	v_add_f32_e32 v92, v92, v93
	v_mov_b32_e32 v250, v92
	v_lshlrev_b32_e32 v92, 16, v84
	v_and_b32_e32 v84, 0xffff0000, v84
	s_waitcnt lgkmcnt(0)
	v_lshlrev_b32_e32 v93, 16, v85
	v_and_b32_e32 v85, 0xffff0000, v85
	v_mul_f32_e32 v84, v113, v84
	v_mul_f32_e32 v85, v115, v85
	v_lshlrev_b32_e32 v94, 16, v86
	v_and_b32_e32 v86, 0xffff0000, v86
	v_fmac_f32_e32 v84, v112, v92
	v_fmac_f32_e32 v85, v114, v93
	v_add_f32_e32 v84, v84, v85
	v_mul_f32_e32 v85, v109, v86
	v_lshlrev_b32_e32 v95, 16, v87
	v_and_b32_e32 v87, 0xffff0000, v87
	v_fmac_f32_e32 v85, v108, v94
	v_add_f32_e32 v84, v84, v85
	v_mul_f32_e32 v85, v111, v87
	v_fmac_f32_e32 v85, v110, v95
	v_and_b32_e32 v86, 0xffff0000, v88
	v_add_f32_e32 v84, v85, v84
	v_lshlrev_b32_e32 v85, 16, v88
	v_and_b32_e32 v88, 0xffff0000, v89
	v_mul_f32_e32 v86, v121, v86
	v_lshlrev_b32_e32 v87, 16, v89
	v_fmac_f32_e32 v86, v120, v85
	v_mul_f32_e32 v85, v123, v88
	v_lshlrev_b32_e32 v89, 16, v90
	v_and_b32_e32 v90, 0xffff0000, v90
	v_fmac_f32_e32 v85, v122, v87
	v_add_f32_e32 v85, v86, v85
	v_mul_f32_e32 v86, v117, v90
	v_lshlrev_b32_e32 v92, 16, v91
	v_and_b32_e32 v91, 0xffff0000, v91
	v_fmac_f32_e32 v86, v116, v89
	v_add_f32_e32 v85, v85, v86
	v_mul_f32_e32 v86, v119, v91
	v_fmac_f32_e32 v86, v118, v92
	v_add_f32_e32 v84, 0, v84
	v_add_f32_e32 v85, v86, v85
	v_add_f32_e32 v84, v84, v85
	v_mov_b32_e32 v251, v84
	v_lshlrev_b32_e32 v84, 16, v76
	v_and_b32_e32 v76, 0xffff0000, v76
	s_waitcnt lgkmcnt(0)
	v_lshlrev_b32_e32 v85, 16, v77
	v_and_b32_e32 v77, 0xffff0000, v77
	v_mul_f32_e32 v76, v113, v76
	v_mul_f32_e32 v77, v115, v77
	v_lshlrev_b32_e32 v86, 16, v78
	v_and_b32_e32 v78, 0xffff0000, v78
	v_fmac_f32_e32 v76, v112, v84
	v_fmac_f32_e32 v77, v114, v85
	v_add_f32_e32 v76, v76, v77
	v_mul_f32_e32 v77, v109, v78
	v_lshlrev_b32_e32 v87, 16, v79
	v_and_b32_e32 v79, 0xffff0000, v79
	v_fmac_f32_e32 v77, v108, v86
	v_add_f32_e32 v76, v76, v77
	v_mul_f32_e32 v77, v111, v79
	v_fmac_f32_e32 v77, v110, v87
	v_and_b32_e32 v78, 0xffff0000, v80
	v_add_f32_e32 v76, v77, v76
	v_lshlrev_b32_e32 v77, 16, v80
	v_and_b32_e32 v80, 0xffff0000, v81
	v_mul_f32_e32 v78, v121, v78
	v_lshlrev_b32_e32 v79, 16, v81
	v_fmac_f32_e32 v78, v120, v77
	v_mul_f32_e32 v77, v123, v80
	v_lshlrev_b32_e32 v81, 16, v82
	v_and_b32_e32 v82, 0xffff0000, v82
	v_fmac_f32_e32 v77, v122, v79
	v_add_f32_e32 v77, v78, v77
	v_mul_f32_e32 v78, v117, v82
	v_lshlrev_b32_e32 v84, 16, v83
	v_and_b32_e32 v83, 0xffff0000, v83
	v_fmac_f32_e32 v78, v116, v81
	v_add_f32_e32 v77, v77, v78
	v_mul_f32_e32 v78, v119, v83
	v_fmac_f32_e32 v78, v118, v84
	v_add_f32_e32 v76, 0, v76
	v_add_f32_e32 v77, v78, v77
	v_add_f32_e32 v76, v76, v77
	ds_bpermute_b32 v253, v209, v250
	ds_bpermute_b32 v254, v209, v251
	ds_bpermute_b32 v77, v209, v76
	s_waitcnt lgkmcnt(0)
	v_add_f32_e32 v250, v250, v253
	v_add_f32_e32 v251, v251, v254
	v_add_f32_e32 v76, v76, v77
	ds_bpermute_b32 v253, v210, v250
	ds_bpermute_b32 v254, v210, v251
	ds_bpermute_b32 v77, v210, v76
	s_and_saveexec_b64 s[74:75], s[8:9]
	s_cbranch_execz .LBB0_892
	s_waitcnt lgkmcnt(0)
	v_add_f32_e32 v250, v250, v253
	v_add_f32_e32 v251, v251, v254
	v_add_f32_e32 v76, v76, v77
	ds_read_b32 v253, v219 offset:64
	ds_read_b32 v254, v219 offset:128
	ds_read_b32 v77, v219 offset:192
	s_waitcnt lgkmcnt(0)
	v_fmac_f32_e32 v250, v148, v253
	v_fmac_f32_e32 v251, v148, v254
	v_fmac_f32_e32 v76, v148, v77
	ds_write_b32 v219, v250 offset:64
	ds_write_b32 v219, v251 offset:128
	ds_write_b32 v219, v76 offset:192

.LBB0_894:
	s_or_b64 exec, exec, s[74:75]
	v_add_u32_e32 v76, s93, v221
	v_lshl_or_b32 v148, v76, 8, v217
	s_waitcnt lgkmcnt(0)
	v_lshl_add_u64 v[76:77], s[60:61], 0, v[148:149]
	v_or_b32_e32 v148, 0x80, v148
	flat_load_dwordx4 v[120:123], v[76:77]
	flat_load_dwordx4 v[116:119], v[76:77] offset:16
	v_lshl_add_u64 v[76:77], s[60:61], 0, v[148:149]
	flat_load_dwordx4 v[80:83], v[76:77]
	s_nop 0
	flat_load_dwordx4 v[76:79], v[76:77] offset:16
	s_waitcnt lgkmcnt(0)
	s_barrier
	v_add_u32_e32 v254, 0x10000, v226
	ds_read_b128 v[84:87], v226
	ds_read_b128 v[88:91], v226 offset:16384
	ds_read_b128 v[92:95], v226 offset:32768
	ds_read_b128 v[96:99], v226 offset:49152
	ds_read_b128 v[100:103], v254
	ds_read_b128 v[104:107], v254 offset:16384
	ds_read_b128 v[108:111], v254 offset:32768
	ds_read_b128 v[112:115], v254 offset:49152
	ds_read_b128 v[234:237], v226 offset:1024
	ds_read_b128 v[238:241], v226 offset:17408
	ds_read_b128 v[242:245], v226 offset:33792
	ds_read_b128 v[246:249], v226 offset:50176
	ds_read_b128 v[250:253], v254 offset:1024
	s_waitcnt lgkmcnt(5)
	v_pk_add_f32 v[84:85], v[84:85], v[88:89]
	v_pk_add_f32 v[86:87], v[86:87], v[90:91]
	v_pk_add_f32 v[84:85], v[84:85], v[92:93]
	v_pk_add_f32 v[86:87], v[86:87], v[94:95]
	v_pk_add_f32 v[84:85], v[84:85], v[96:97]
	v_pk_add_f32 v[86:87], v[86:87], v[98:99]
	v_pk_add_f32 v[84:85], v[84:85], v[100:101]
	v_pk_add_f32 v[86:87], v[86:87], v[102:103]
	v_pk_add_f32 v[84:85], v[84:85], v[104:105]
	v_pk_add_f32 v[86:87], v[86:87], v[106:107]
	v_pk_add_f32 v[84:85], v[84:85], v[108:109]
	v_pk_add_f32 v[86:87], v[86:87], v[110:111]
	v_pk_add_f32 v[128:129], v[84:85], v[112:113]
	v_pk_add_f32 v[124:125], v[86:87], v[114:115]
	ds_read_b128 v[88:91], v254 offset:17408
	ds_read_b128 v[92:95], v254 offset:33792
	ds_read_b128 v[96:99], v254 offset:50176
	s_waitcnt lgkmcnt(3)
	v_pk_add_f32 v[234:235], v[234:235], v[238:239]
	v_pk_add_f32 v[236:237], v[236:237], v[240:241]
	v_pk_add_f32 v[234:235], v[234:235], v[242:243]
	v_pk_add_f32 v[236:237], v[236:237], v[244:245]
	v_pk_add_f32 v[234:235], v[234:235], v[246:247]
	v_pk_add_f32 v[236:237], v[236:237], v[248:249]
	v_pk_add_f32 v[234:235], v[234:235], v[250:251]
	v_pk_add_f32 v[236:237], v[236:237], v[252:253]
	s_waitcnt lgkmcnt(0)
	v_pk_add_f32 v[234:235], v[234:235], v[88:89]
	v_pk_add_f32 v[236:237], v[236:237], v[90:91]
	v_pk_add_f32 v[234:235], v[234:235], v[92:93]
	v_pk_add_f32 v[236:237], v[236:237], v[94:95]
	v_pk_add_f32 v[130:131], v[234:235], v[96:97]
	v_pk_add_f32 v[126:127], v[236:237], v[98:99]

.LBB0_904:
	s_or_b64 exec, exec, s[74:75]
	v_add_f32_e32 v100, 0, v100
	v_add_f32_e32 v84, v100, v84
	v_add_f32_e32 v84, v84, v88
	v_add_f32_e32 v88, 0, v101
	v_add_f32_e32 v85, v88, v85
	v_add_f32_e32 v85, v85, v89
	v_add_f32_e32 v85, v85, v93
	v_add_f32_e32 v85, v85, v97
	v_add_f32_e32 v85, v85, v105
	v_add_f32_e32 v85, v85, v109
	v_add_f32_e32 v100, v85, v113
	v_add_f32_e32 v85, 0, v102
	v_add_f32_e32 v85, v85, v86
	v_add_f32_e32 v85, v85, v90
	v_add_f32_e32 v85, v85, v94
	v_add_f32_e32 v85, v85, v98
	v_add_f32_e32 v85, v85, v106
	v_add_f32_e32 v85, v85, v110
	v_add_f32_e32 v101, v85, v114
	v_add_f32_e32 v85, 0, v103
	v_add_f32_e32 v85, v85, v87
	v_add_f32_e32 v84, v84, v92
	v_add_f32_e32 v85, v85, v91
	s_waitcnt lgkmcnt(0)
	v_add_f32_e32 v84, v84, v96
	v_add_f32_e32 v85, v85, v95
	ds_read_b128 v[86:89], v227 offset:768
	ds_read_b128 v[90:93], v230 offset:1280
	ds_read_b128 v[94:97], v227 offset:1024
	v_add_f32_e32 v84, v84, v104
	v_add_f32_e32 v85, v85, v99
	v_add_f32_e32 v84, v84, v108
	v_add_f32_e32 v85, v85, v107
	v_add_f32_e32 v84, v84, v112
	v_add_f32_e32 v85, v85, v111
	v_add_f32_e32 v102, v85, v115
	s_waitcnt lgkmcnt(1)
	v_fma_f32 v84, v84, v86, v90
	s_waitcnt lgkmcnt(0)
	v_max_f32_e32 v85, v94, v94
	v_max_f32_e64 v84, |v84|, v85
	v_div_scale_f32 v85, s[74:75], v84, v84, 1.0
	v_rcp_f32_e32 v90, v85
	v_fma_f32 v76, v128, v86, v76
	v_fma_f32 v77, v129, v87, v77
	v_fma_f32 v78, v124, v88, v78
	v_fma_f32 v94, -v85, v90, 1.0
	v_fmac_f32_e32 v90, v94, v90
	v_div_scale_f32 v94, vcc, 1.0, v84, 1.0
	v_mul_f32_e32 v98, v94, v90
	v_fma_f32 v99, -v85, v98, v94
	v_fmac_f32_e32 v98, v99, v90
	v_fma_f32 v85, -v85, v98, v94
	v_div_fmas_f32 v85, v85, v90, v98
	v_div_fixup_f32 v90, v85, v84, 1.0
	v_add_u32_e32 v84, s92, v224
	v_ashrrev_i32_e32 v85, 31, v84
	v_mul_f32_e32 v94, v76, v90
	v_lshlrev_b64 v[98:99], 12, v[84:85]
	v_bfe_u32 v103, v94, 16, 1
	v_add3_u32 v103, v94, v103, s85
	v_lshl_add_u64 v[98:99], v[166:167], 0, v[98:99]
	flat_store_short_d16_hi v[98:99], v103
	v_fma_f32 v103, v76, v90, 0
	v_fma_f32 v76, v130, v86, v80
	v_mul_f32_e32 v80, v76, v90
	v_bfe_u32 v86, v80, 16, 1
	v_add3_u32 v86, v80, v86, s85
	flat_store_short_d16_hi v[98:99], v86 offset:32
	v_fmac_f32_e32 v103, v76, v90
	v_mul_f32_e32 v98, v80, v80
	v_fma_f32 v76, v100, v87, v91
	v_max_f32_e32 v80, v95, v95
	v_max_f32_e64 v76, |v76|, v80
	v_div_scale_f32 v80, s[74:75], v76, v76, 1.0
	v_rcp_f32_e32 v86, v80
	v_fmac_f32_e32 v98, v94, v94
	v_fmac_f32_e32 v93, v102, v89
	v_fmac_f32_e32 v79, v125, v89
	v_fma_f32 v90, -v80, v86, 1.0
	v_fmac_f32_e32 v86, v90, v86
	v_div_scale_f32 v90, vcc, 1.0, v76, 1.0
	v_mul_f32_e32 v91, v90, v86
	v_fma_f32 v94, -v80, v91, v90
	v_fmac_f32_e32 v91, v94, v86
	v_fma_f32 v80, -v80, v91, v90
	v_div_fmas_f32 v80, v80, v86, v91
	v_div_fixup_f32 v76, v80, v76, 1.0
	v_or_b32_e32 v80, 1, v224
	v_add_u32_e32 v90, s92, v80
	v_ashrrev_i32_e32 v91, 31, v90
	v_mul_f32_e32 v77, v77, v76
	v_lshlrev_b64 v[90:91], 12, v[90:91]
	v_bfe_u32 v80, v77, 16, 1
	v_add3_u32 v80, v77, v80, s85
	v_lshl_add_u64 v[90:91], v[166:167], 0, v[90:91]
	flat_store_short_d16_hi v[90:91], v80
	v_fma_f32 v80, v131, v87, v81
	v_mul_f32_e32 v80, v80, v76
	v_bfe_u32 v76, v80, 16, 1
	v_add3_u32 v76, v80, v76, s85
	flat_store_short_d16_hi v[90:91], v76 offset:32
	v_fma_f32 v76, v101, v88, v92
	v_max_f32_e32 v81, v96, v96
	v_max_f32_e64 v76, |v76|, v81
	v_div_scale_f32 v81, s[74:75], v76, v76, 1.0
	v_rcp_f32_e32 v86, v81
	v_fmac_f32_e32 v83, v127, v89
	v_fma_f32 v87, -v81, v86, 1.0
	v_fmac_f32_e32 v86, v87, v86
	v_div_scale_f32 v87, vcc, 1.0, v76, 1.0
	v_mul_f32_e32 v90, v87, v86
	v_fma_f32 v91, -v81, v90, v87
	v_fmac_f32_e32 v90, v91, v86
	v_fma_f32 v81, -v81, v90, v87
	v_div_fmas_f32 v81, v81, v86, v90
	v_div_fixup_f32 v76, v81, v76, 1.0
	v_or_b32_e32 v81, 2, v224
	v_add_u32_e32 v86, s92, v81
	v_ashrrev_i32_e32 v87, 31, v86
	v_mul_f32_e32 v78, v78, v76
	v_lshlrev_b64 v[86:87], 12, v[86:87]
	v_bfe_u32 v81, v78, 16, 1
	v_add3_u32 v81, v78, v81, s85
	v_lshl_add_u64 v[86:87], v[166:167], 0, v[86:87]
	flat_store_short_d16_hi v[86:87], v81
	v_fma_f32 v81, v126, v88, v82
	v_mul_f32_e32 v81, v81, v76
	v_bfe_u32 v76, v81, 16, 1
	v_add3_u32 v76, v81, v76, s85
	flat_store_short_d16_hi v[86:87], v76 offset:32
	v_max_f32_e32 v76, v97, v97
	v_max_f32_e64 v76, |v93|, v76
	v_div_scale_f32 v82, s[74:75], v76, v76, 1.0
	v_rcp_f32_e32 v86, v82
	s_nop 0
	v_fma_f32 v87, -v82, v86, 1.0
	v_fmac_f32_e32 v86, v87, v86
	v_div_scale_f32 v87, vcc, 1.0, v76, 1.0
	v_mul_f32_e32 v88, v87, v86
	v_fma_f32 v90, -v82, v88, v87
	v_fmac_f32_e32 v88, v90, v86
	v_fma_f32 v82, -v82, v88, v87
	v_div_fmas_f32 v82, v82, v86, v88
	v_div_fixup_f32 v82, v82, v76, 1.0
	v_add_u32_e32 v86, s92, v228
	v_ashrrev_i32_e32 v87, 31, v86
	v_mul_f32_e32 v76, v79, v82
	v_lshlrev_b64 v[86:87], 12, v[86:87]
	v_bfe_u32 v79, v76, 16, 1
	v_add3_u32 v79, v76, v79, s85
	v_lshl_add_u64 v[86:87], v[166:167], 0, v[86:87]
	flat_store_short_d16_hi v[86:87], v79
	v_mul_f32_e32 v79, v83, v82
	v_bfe_u32 v82, v79, 16, 1
	v_add3_u32 v82, v79, v82, s85
	flat_store_short_d16_hi v[86:87], v82 offset:32
	s_nop 1
	v_add_f32_dpp v82, v103, v103 quad_perm:[1,0,3,2] row_mask:0xf bank_mask:0xf
	v_add_f32_dpp v83, v98, v98 quad_perm:[1,0,3,2] row_mask:0xf bank_mask:0xf
	s_nop 0
	v_add_f32_dpp v82, v82, v82 quad_perm:[2,3,0,1] row_mask:0xf bank_mask:0xf
	v_add_f32_dpp v83, v83, v83 quad_perm:[2,3,0,1] row_mask:0xf bank_mask:0xf
	s_nop 0
	v_add_f32_dpp v82, v82, v82 row_half_mirror row_mask:0xf bank_mask:0xf
	v_add_f32_dpp v83, v83, v83 row_half_mirror row_mask:0xf bank_mask:0xf
	s_nop 0
	v_add_f32_dpp v82, v82, v82 row_mirror row_mask:0xf bank_mask:0xf
	v_add_f32_dpp v83, v83, v83 row_mirror row_mask:0xf bank_mask:0xf
	s_and_saveexec_b64 s[74:75], s[12:13]
	s_cbranch_execz .LBB0_906
	v_lshlrev_b64 v[88:89], 5, v[84:85]
	v_lshl_add_u64 v[88:89], s[70:71], 0, v[88:89]
	s_waitcnt lgkmcnt(0)
	flat_atomic_add_f32 v[88:89], v82
	flat_atomic_add_f32 v[88:89], v83 offset:4
.LBB0_906:
	s_or_b64 exec, exec, s[74:75]
	v_add_f32_e32 v82, 0, v77
	v_add_f32_e32 v82, v80, v82
	v_mul_f32_e32 v80, v80, v80
	v_fmac_f32_e32 v80, v77, v77
	s_nop 1
	v_add_f32_dpp v77, v82, v82 quad_perm:[1,0,3,2] row_mask:0xf bank_mask:0xf
	v_add_f32_dpp v80, v80, v80 quad_perm:[1,0,3,2] row_mask:0xf bank_mask:0xf
	s_nop 0
	v_add_f32_dpp v77, v77, v77 quad_perm:[2,3,0,1] row_mask:0xf bank_mask:0xf
	v_add_f32_dpp v80, v80, v80 quad_perm:[2,3,0,1] row_mask:0xf bank_mask:0xf
	s_nop 0
	v_add_f32_dpp v77, v77, v77 row_half_mirror row_mask:0xf bank_mask:0xf
	v_add_f32_dpp v80, v80, v80 row_half_mirror row_mask:0xf bank_mask:0xf
	s_nop 0
	v_add_f32_dpp v77, v77, v77 row_mirror row_mask:0xf bank_mask:0xf
	v_add_f32_dpp v80, v80, v80 row_mirror row_mask:0xf bank_mask:0xf
	s_and_saveexec_b64 s[74:75], s[12:13]
	s_cbranch_execz .LBB0_908
	s_waitcnt lgkmcnt(0)
	v_or_b32_e32 v82, 1, v84
	v_ashrrev_i32_e32 v83, 31, v82
	v_lshlrev_b64 v[82:83], 5, v[82:83]
	v_lshl_add_u64 v[82:83], s[70:71], 0, v[82:83]
	flat_atomic_add_f32 v[82:83], v77
	flat_atomic_add_f32 v[82:83], v80 offset:4
.LBB0_908:
	s_or_b64 exec, exec, s[74:75]
	v_add_f32_e32 v77, 0, v78
	v_mul_f32_e32 v80, v81, v81
	v_add_f32_e32 v77, v81, v77
	v_fmac_f32_e32 v80, v78, v78
	s_nop 1
	v_add_f32_dpp v77, v77, v77 quad_perm:[1,0,3,2] row_mask:0xf bank_mask:0xf
	v_add_f32_dpp v78, v80, v80 quad_perm:[1,0,3,2] row_mask:0xf bank_mask:0xf
	s_nop 0
	v_add_f32_dpp v77, v77, v77 quad_perm:[2,3,0,1] row_mask:0xf bank_mask:0xf
	v_add_f32_dpp v78, v78, v78 quad_perm:[2,3,0,1] row_mask:0xf bank_mask:0xf
	s_nop 0
	v_add_f32_dpp v77, v77, v77 row_half_mirror row_mask:0xf bank_mask:0xf
	v_add_f32_dpp v78, v78, v78 row_half_mirror row_mask:0xf bank_mask:0xf
	s_nop 0
	v_add_f32_dpp v77, v77, v77 row_mirror row_mask:0xf bank_mask:0xf
	v_add_f32_dpp v78, v78, v78 row_mirror row_mask:0xf bank_mask:0xf
	s_and_saveexec_b64 s[74:75], s[12:13]
	s_cbranch_execz .LBB0_910
	s_waitcnt lgkmcnt(0)
	v_or_b32_e32 v80, 2, v84
	v_ashrrev_i32_e32 v81, 31, v80
	v_lshlrev_b64 v[80:81], 5, v[80:81]
	v_lshl_add_u64 v[80:81], s[70:71], 0, v[80:81]
	flat_atomic_add_f32 v[80:81], v77
	flat_atomic_add_f32 v[80:81], v78 offset:4
.LBB0_910:
	s_or_b64 exec, exec, s[74:75]
	v_add_f32_e32 v77, 0, v76
	v_mul_f32_e32 v78, v79, v79
	v_add_f32_e32 v77, v79, v77
	v_fmac_f32_e32 v78, v76, v76
	s_nop 1
	v_add_f32_dpp v76, v77, v77 quad_perm:[1,0,3,2] row_mask:0xf bank_mask:0xf
	v_add_f32_dpp v77, v78, v78 quad_perm:[1,0,3,2] row_mask:0xf bank_mask:0xf
	s_nop 0
	v_add_f32_dpp v76, v76, v76 quad_perm:[2,3,0,1] row_mask:0xf bank_mask:0xf
	v_add_f32_dpp v77, v77, v77 quad_perm:[2,3,0,1] row_mask:0xf bank_mask:0xf
	s_nop 0
	v_add_f32_dpp v76, v76, v76 row_half_mirror row_mask:0xf bank_mask:0xf
	v_add_f32_dpp v77, v77, v77 row_half_mirror row_mask:0xf bank_mask:0xf
	s_nop 0
	v_add_f32_dpp v76, v76, v76 row_mirror row_mask:0xf bank_mask:0xf
	v_add_f32_dpp v77, v77, v77 row_mirror row_mask:0xf bank_mask:0xf
	s_and_saveexec_b64 s[74:75], s[12:13]
	s_cbranch_execz .LBB0_912
	s_waitcnt lgkmcnt(0)
	v_mov_b32_e32 v78, v76
	v_or_b32_e32 v76, 3, v84
	v_mov_b32_e32 v79, v77
	v_ashrrev_i32_e32 v77, 31, v76
	v_lshlrev_b64 v[76:77], 5, v[76:77]
	v_lshl_add_u64 v[76:77], s[70:71], 0, v[76:77]
	flat_atomic_add_f32 v[76:77], v78
	flat_atomic_add_f32 v[76:77], v79 offset:4
